# phase0 x->bf16 conversion loop 4 iterations in flight + band epilogue rcp/16 loads in flight + LN residual 4 groups in flight
# baseline (speedup 1.0000x reference)
.Lx4_loop:
	v_lshl_add_u64 v[18:19], v[8:9], 0, s[92:93]
	v_lshl_add_u64 v[18:19], v[18:19], 0, s[92:93]
	v_lshl_add_u64 v[18:19], v[18:19], 0, s[92:93]
	s_mov_b64 s[6:7], 0x1fffff
	v_cmp_ge_u64_e32 vcc, s[6:7], v[18:19]
	s_andn2_b64 s[6:7], exec, vcc
	s_cbranch_scc1 .LBB0_707
	global_load_dwordx4 v[20:23], v[6:7], off offset:-16 nt
	global_load_dwordx4 v[24:27], v[6:7], off nt
	v_lshl_add_u64 v[52:53], v[6:7], 0, s[12:13]
	global_load_dwordx4 v[28:31], v[52:53], off offset:-16 nt
	global_load_dwordx4 v[32:35], v[52:53], off nt
	v_lshl_add_u64 v[52:53], v[52:53], 0, s[12:13]
	global_load_dwordx4 v[36:39], v[52:53], off offset:-16 nt
	global_load_dwordx4 v[40:43], v[52:53], off nt
	v_lshl_add_u64 v[52:53], v[52:53], 0, s[12:13]
	global_load_dwordx4 v[44:47], v[52:53], off offset:-16 nt
	global_load_dwordx4 v[48:51], v[52:53], off nt
	v_lshl_add_u64 v[6:7], v[52:53], 0, s[12:13]
	v_lshl_add_u64 v[8:9], v[18:19], 0, s[92:93]
	s_waitcnt vmcnt(6)
	v_cvt_pk_bf16_f32 v10, v20, v21
	v_cvt_pk_bf16_f32 v11, v22, v23
	v_cvt_pk_bf16_f32 v12, v24, v25
	v_cvt_pk_bf16_f32 v13, v26, v27
	global_store_dwordx4 v[4:5], v[10:13], off
	v_lshl_add_u64 v[4:5], v[4:5], 0, s[26:27]
	s_waitcnt vmcnt(5)
	v_cvt_pk_bf16_f32 v54, v28, v29
	v_cvt_pk_bf16_f32 v55, v30, v31
	v_cvt_pk_bf16_f32 v56, v32, v33
	v_cvt_pk_bf16_f32 v57, v34, v35
	global_store_dwordx4 v[4:5], v[54:57], off
	v_lshl_add_u64 v[4:5], v[4:5], 0, s[26:27]
	s_waitcnt vmcnt(4)
	v_cvt_pk_bf16_f32 v58, v36, v37
	v_cvt_pk_bf16_f32 v59, v38, v39
	v_cvt_pk_bf16_f32 v60, v40, v41
	v_cvt_pk_bf16_f32 v61, v42, v43
	global_store_dwordx4 v[4:5], v[58:61], off
	v_lshl_add_u64 v[4:5], v[4:5], 0, s[26:27]
	s_waitcnt vmcnt(3)
	v_cvt_pk_bf16_f32 v62, v44, v45
	v_cvt_pk_bf16_f32 v63, v46, v47
	v_cvt_pk_bf16_f32 v64, v48, v49
	v_cvt_pk_bf16_f32 v65, v50, v51
	global_store_dwordx4 v[4:5], v[62:65], off
	v_lshl_add_u64 v[4:5], v[4:5], 0, s[26:27]
	s_mov_b64 s[6:7], 0x1fffff
	v_cmp_lt_u64_e32 vcc, s[6:7], v[8:9]
	s_andn2_b64 exec, exec, vcc
	s_cbranch_execnz .Lx4_loop
	s_branch .LBB0_708
